# scan phase sample-row tasks (the phase's critical path): the 16 carried-state loads issued together with counted waits; per-task constant loads issued together
# speedup vs baseline: 1.0039x; 1.0039x over previous
; __device__ __forceinline__ void scan_phase(KP p, int l, LAS unsigned char* lds) {
;     ...
;         LDS_WAIT();
;         {
;             const int ch = hc0 + lane;
; #pragma unroll
;             for (int k = 0; k < 4; ++k) CST[k * 64 + lane] = p->in[14][(size_t)(l * 4 + k) * D + ch];
;             CST[4 * 64 + lane] = p->in[15][l * D + ch]; CST[5 * 64 + lane] = p->in[17][l * D + ch]; CST[6 * 64 + lane] = p->in[19][l * D + ch]; CST[7 * 64 + lane] = SP[ch];
;         }
;         bf16x8 Wa[4][2], Wx[4][2];
; #pragma unroll
;         for (int n = 0; n < 4; ++n)
; #pragma unroll
;             for (int s = 0; s < 2; ++s) { const size_t o = (size_t)head * 4096 + (16 * n + fr) * 64 + 32 * s + 8 * fq;
;                 Wa[n][s] = *(const bf16x8*)((const bf16_t*)(p->ws + WS_RGA) + o); Wx[n][s] = *(const bf16x8*)((const bf16_t*)(p->ws + WS_RGX) + o); }
;         if (ck < 128) {
;             const int b = ck >> 4, q = ck & 15, tile0 = b * 129 + 8 * q;
;             float Hc[4], Pc[4];
; #pragma unroll
;             for (int n = 0; n < 4; ++n) { Hc[n] = 0.f; Pc[n] = 1.f; }
;             for (int tt = 0; tt < 8; tt += 2) scan_tiles<2>(p, l, P, HLOC, PCUM, XC, CST, Wa, Wx, b, hc0, (tile0 + tt) * 16, lane, fr, fq, Hc, Pc);
;             if (q == 15) scan_tiles<1>(p, l, P, HLOC, PCUM, XC, CST, Wa, Wx, b, hc0, (tile0 + 8) * 16, lane, fr, fq, Hc, Pc);
;             if (fq == 0) {
; #pragma unroll
;                 for (int n = 0; n < 4; ++n) { const int ch = hc0 + 16 * n + fr; SUMM[(size_t)ck * 2 * D + ch] = Pc[n]; SUMM[(size_t)ck * 2 * D + D + ch] = Hc[n]; } }
;         } else {
;             const int m0 = (1032 + (ck - 128)) * 16;
;             LDS_WAIT();
;             {   const int rr = lane >> 2, cb = lane & 3, cl = cb * 16, m = m0 + rr, sb = m - MP;
;                 float xv[4][16];
;                 const float* st = p->in[3] + ((size_t)(l * MS + sb) * 3) * D + hc0 + cl;
; #pragma unroll
;                 for (int k = 0; k < 3; ++k)
; #pragma unroll
;                     for (int e = 0; e < 16; e += 4) { const f32x4 v = *(const f32x4*)(st + (size_t)k * D + e); xv[k][e] = v[0]; xv[k][e + 1] = v[1]; xv[k][e + 2] = v[2]; xv[k][e + 3] = v[3]; }
;                 const bf16_t* src = P + (size_t)m * DP + C_XR + hc0 + cl;
;                 float f0[8], f1[8]; unpack8(*(const u32x4*)src, f0); unpack8(*(const u32x4*)(src + 8), f1);
; #pragma unroll
.LBB0_331:
	s_and_b32 s16, s54, 15
	s_waitcnt lgkmcnt(0)
	s_lshl_b32 s75, s16, 6
	s_load_dwordx4 s[12:15], s[58:59], 0x70
	s_load_dwordx2 s[10:11], s[58:59], 0x88
	s_load_dwordx2 s[18:19], s[58:59], 0x98
	s_waitcnt vmcnt(1)
	v_or_b32_e32 v6, s75, v205
	v_lshlrev_b32_e32 v0, 2, v6
	s_waitcnt vmcnt(0) lgkmcnt(0)
	v_lshl_add_u64 v[2:3], s[12:13], 0, v[0:1]
	v_lshl_add_u64 v[2:3], v[2:3], 0, s[68:69]
	v_add_co_u32_e32 v4, vcc, s43, v2
	global_load_dword v7, v[2:3], off
	s_nop 0
	v_addc_co_u32_e32 v5, vcc, 0, v3, vcc
	global_load_dword v8, v[4:5], off offset:-4096
	v_add_co_u32_e32 v2, vcc, s23, v2
	global_load_dword v4, v[4:5], off
	s_nop 0
	v_addc_co_u32_e32 v3, vcc, 0, v3, vcc
	global_load_dword v2, v[2:3], off
	v_or_b32_e32 v246, s77, v6
	v_lshlrev_b32_e32 v246, 2, v246
	global_load_dword v247, v246, s[14:15]
	global_load_dword v248, v246, s[10:11]
	global_load_dword v249, v246, s[18:19]
	global_load_dword v250, v0, s[66:67]
	v_mov_b32_e32 v3, v1
	s_ashr_i32 s74, s54, 4
	s_cmpk_gt_i32 s74, 0x7f
	v_add_u32_e32 v241, v232, v231
	s_waitcnt vmcnt(6)
	ds_write2st64_b32 v225, v7, v8 offset0:34 offset1:35
	s_waitcnt vmcnt(4)
	ds_write2st64_b32 v225, v4, v2 offset0:36 offset1:37
	v_or_b32_e32 v2, s77, v6
	v_lshlrev_b64 v[2:3], 2, v[2:3]
	v_lshl_add_u64 v[4:5], s[14:15], 0, v[2:3]
	v_lshl_add_u64 v[4:5], s[10:11], 0, v[2:3]
	v_lshl_add_u64 v[2:3], s[18:19], 0, v[2:3]
	s_mov_b64 s[10:11], -1
	s_waitcnt vmcnt(2)
	v_mov_b32_e32 v6, v247
	v_mov_b32_e32 v4, v248
	ds_write2st64_b32 v225, v6, v4 offset0:38 offset1:39
	s_nop 0
	s_waitcnt vmcnt(0)
	v_mov_b32_e32 v2, v249
	v_mov_b32_e32 v0, v250
	ds_write2st64_b32 v225, v2, v0 offset0:40 offset1:41
	v_lshl_or_b32 v0, s16, 13, v238
	v_or_b32_e32 v2, 64, v0
	global_load_dwordx4 v[34:37], v0, s[70:71]
	global_load_dwordx4 v[38:41], v0, s[72:73]
	global_load_dwordx4 v[10:13], v2, s[70:71]
	global_load_dwordx4 v[14:17], v2, s[72:73]
	v_or_b32_e32 v2, 0x800, v0
	global_load_dwordx4 v[42:45], v2, s[70:71]
	global_load_dwordx4 v[46:49], v2, s[72:73]
	v_or_b32_e32 v2, 0x840, v0
	global_load_dwordx4 v[22:25], v2, s[70:71]
	global_load_dwordx4 v[26:29], v2, s[72:73]
	v_or_b32_e32 v2, 0x1000, v0
	global_load_dwordx4 v[50:53], v2, s[70:71]
	global_load_dwordx4 v[54:57], v2, s[72:73]
	v_or_b32_e32 v2, 0x1040, v0
	global_load_dwordx4 v[30:33], v2, s[70:71]
	global_load_dwordx4 v[18:21], v2, s[72:73]
	v_or_b32_e32 v2, 0x1800, v0
	v_or_b32_e32 v0, 0x1840, v0
	global_load_dwordx4 v[62:65], v2, s[70:71]
	global_load_dwordx4 v[58:61], v2, s[72:73]
	global_load_dwordx4 v[6:9], v0, s[70:71]
	s_nop 0
	global_load_dwordx4 v[2:5], v0, s[72:73]
	v_lshlrev_b32_e32 v0, 1, v206
	s_cbranch_scc0 .LBB0_333
	s_waitcnt lgkmcnt(0)
	s_load_dwordx4 s[12:15], s[58:59], 0x18
	s_and_b32 s10, s54, -16
	s_add_i32 s11, s10, 0x3880
	v_or_b32_e32 v106, s11, v226
	v_add_u32_e32 v126, s78, v106
	s_waitcnt lgkmcnt(0)
	v_mov_b64_e32 v[66:67], s[12:13]
	v_mad_i64_i32 v[66:67], s[12:13], v126, s23, v[66:67]
	s_lshl_b32 s16, s75, 2
	v_lshl_add_u64 v[66:67], v[66:67], 0, s[16:17]
	v_lshlrev_b32_e32 v122, 2, v206
	v_mov_b32_e32 v123, v1
	v_lshl_add_u64 v[70:71], v[66:67], 0, v[122:123]
	v_add_co_u32_e32 v78, vcc, s43, v70
	v_lshl_add_u64 v[72:73], v[70:71], 0, s[28:29]
	s_nop 0
	v_addc_co_u32_e32 v79, vcc, 0, v71, vcc
	global_load_dwordx4 v[66:69], v[70:71], off offset:48
	global_load_dwordx4 v[82:85], v[70:71], off offset:32
	global_load_dwordx4 v[94:97], v[70:71], off offset:16
	global_load_dwordx4 v[110:113], v[70:71], off
	global_load_dwordx4 v[114:117], v[78:79], off offset:-4096
	global_load_dwordx4 v[74:77], v[72:73], off offset:48
	global_load_dwordx4 v[90:93], v[72:73], off offset:32
	global_load_dwordx4 v[102:105], v[72:73], off offset:16
	v_lshl_add_u64 v[80:81], v[70:71], 0, s[30:31]
	global_load_dwordx4 v[118:121], v[78:79], off
	global_load_dwordx4 v[70:73], v[80:81], off offset:48
	global_load_dwordx4 v[86:89], v[80:81], off offset:32
	global_load_dwordx4 v[98:101], v[80:81], off offset:16
	v_mov_b64_e32 v[78:79], s[60:61]
	v_mad_u64_u32 v[78:79], s[12:13], v106, s33, v[78:79]
	s_lshl_b32 s12, s75, 1
	s_mov_b32 s13, s17
	v_lshl_add_u64 v[78:79], v[78:79], 0, s[12:13]
	v_lshl_add_u64 v[78:79], v[78:79], 0, v[0:1]
	v_lshl_add_u64 v[80:81], v[78:79], 0, s[28:29]
	v_add_co_u32_e32 v78, vcc, s38, v78
	s_nop 1
	v_addc_co_u32_e32 v79, vcc, 0, v79, vcc
	global_load_dwordx4 v[106:109], v[78:79], off
	s_nop 0
	global_load_dwordx4 v[78:81], v[80:81], off offset:16
	s_load_dwordx2 s[12:13], s[58:59], 0xe0
	s_waitcnt lgkmcnt(0)
	v_mov_b64_e32 v[124:125], s[12:13]
	v_mad_i64_i32 v[124:125], s[18:19], v126, s23, v[124:125]
	v_lshl_add_u64 v[124:125], v[124:125], 0, s[16:17]
	v_lshl_add_u64 v[146:147], v[124:125], 0, v[122:123]
	s_mov_b32 s16, 0x45f1000
	v_add_co_u32_e32 v124, vcc, s16, v146
	s_mov_b64 s[18:19], 0x45f0000
	s_nop 0
	v_addc_co_u32_e32 v125, vcc, 0, v147, vcc
	v_lshl_add_u64 v[122:123], v[146:147], 0, s[18:19]
	s_mov_b32 s16, 0x45f2000
	s_mov_b64 s[18:19], 0x4bf0000
	s_waitcnt vmcnt(9)
	global_store_dwordx4 v[124:125], v[114:117], off offset:-4096
	s_waitcnt vmcnt(7)
	global_store_dwordx4 v[122:123], v[102:105], off offset:16
	global_store_dwordx4 v[122:123], v[90:93], off offset:32
	global_store_dwordx4 v[122:123], v[74:77], off offset:48
	s_waitcnt vmcnt(9)
	global_store_dwordx4 v[124:125], v[118:121], off
	s_waitcnt vmcnt(7)
	global_store_dwordx4 v[124:125], v[98:101], off offset:16
	global_store_dwordx4 v[124:125], v[86:89], off offset:32
	global_store_dwordx4 v[124:125], v[70:73], off offset:48
	ds_read_b128 v[122:125], v227 offset:8704
	ds_read_b128 v[126:129], v227 offset:8960
	ds_read_b128 v[130:133], v227 offset:9216
	ds_read_b128 v[134:137], v227 offset:9472
	ds_read_b128 v[138:141], v227 offset:9728
	s_waitcnt lgkmcnt(3)
; #define LAS __attribute__((address_space(3)))
; __device__ __forceinline__ unsigned cvt_pk_bf16(float lo, float hi) { unsigned r; asm volatile("v_cvt_pk_bf16_f32 %0, %1, %2" : "=v"(r) : "v"(lo), "v"(hi)); return r; }
; #define LDS_WAIT() asm volatile("s_waitcnt lgkmcnt(0)" ::: "memory")
; __device__ __forceinline__ void scan_phase(KP p, int l, LAS unsigned char* lds) {
;     ...
; #pragma unroll
;                 for (int e = 0; e < 16; e += 4) {
;                     const f32x4 w0 = *(const LAS f32x4*)(CST + 0 * 64 + cl + e), w1 = *(const LAS f32x4*)(CST + 1 * 64 + cl + e), w2 = *(const LAS f32x4*)(CST + 2 * 64 + cl + e),
;                                 w3 = *(const LAS f32x4*)(CST + 3 * 64 + cl + e), bb = *(const LAS f32x4*)(CST + 4 * 64 + cl + e);
;                     f32x4 r;
; #pragma unroll
;                     for (int q = 0; q < 4; ++q) r[q] = w0[q] * xv[0][e + q] + w1[q] * xv[1][e + q] + w2[q] * xv[2][e + q] + w3[q] * xv[3][e + q] + bb[q];
;                     *(LAS f32x4*)(XC + rr * 68 + cl + e) = r;
;                 }
;             }
;             LDS_WAIT();
;             f32x4 ar[4], ai[4];
; #pragma unroll
;             for (int n = 0; n < 4; ++n) { ar[n] = (f32x4){0.f, 0.f, 0.f, 0.f}; ai[n] = (f32x4){0.f, 0.f, 0.f, 0.f}; }
; #pragma unroll
;             for (int s = 0; s < 2; ++s) {
;                 const f32x4 x0 = *(const LAS f32x4*)(XC + fr * 68 + 32 * s + 8 * fq), x1 = *(const LAS f32x4*)(XC + fr * 68 + 32 * s + 8 * fq + 4);
;                 u32x4 aw; aw.x = cvt_pk_bf16(x0[0], x0[1]); aw.y = cvt_pk_bf16(x0[2], x0[3]); aw.z = cvt_pk_bf16(x1[0], x1[1]); aw.w = cvt_pk_bf16(x1[2], x1[3]);
;                 const bf16x8 af = __builtin_bit_cast(bf16x8, aw);
; #pragma unroll
;                 for (int n = 0; n < 4; ++n) { ar[n] = __builtin_amdgcn_mfma_f32_16x16x32_bf16(af, Wa[n][s], ar[n], 0, 0, 0); ai[n] = __builtin_amdgcn_mfma_f32_16x16x32_bf16(af, Wx[n][s], ai[n], 0, 0, 0); }
;             }
; #pragma unroll
;             for (int n = 0; n < 4; ++n) {
;                 const int cc = 16 * n + fr, ch = hc0 + cc;
;                 const float ba = CST[5 * 64 + cc], bx = CST[6 * 64 + cc], sp = CST[7 * 64 + cc];
; #pragma unroll
;                 for (int j = 0; j < 4; ++j) {
;                     const float xc = XC[(4 * fq + j) * 68 + cc];
;                     const float r = sigmoidf_(ar[n][j] + ba), ig = sigmoidf_(ai[n][j] + bx);
	v_pk_mul_f32 v[116:117], v[116:117], v[128:129]
	v_pk_mul_f32 v[114:115], v[114:115], v[126:127]
	v_pk_fma_f32 v[112:113], v[112:113], v[124:125], v[116:117]
	v_pk_fma_f32 v[110:111], v[110:111], v[122:123], v[114:115]
	s_waitcnt lgkmcnt(2)
	v_pk_fma_f32 v[112:113], v[120:121], v[132:133], v[112:113]
	v_pk_fma_f32 v[110:111], v[118:119], v[130:131], v[110:111]
	s_waitcnt vmcnt(9)
	v_lshlrev_b32_e32 v142, 16, v106
	v_and_b32_e32 v143, 0xffff0000, v106
	v_lshlrev_b32_e32 v144, 16, v107
	v_and_b32_e32 v145, 0xffff0000, v107
	v_add_co_u32_e32 v106, vcc, s16, v146
	s_waitcnt lgkmcnt(1)
	v_pk_fma_f32 v[112:113], v[136:137], v[144:145], v[112:113]
	v_pk_fma_f32 v[110:111], v[134:135], v[142:143], v[110:111]
	v_addc_co_u32_e32 v107, vcc, 0, v147, vcc
	s_waitcnt lgkmcnt(0)
	v_pk_add_f32 v[112:113], v[140:141], v[112:113]
	v_pk_add_f32 v[110:111], v[138:139], v[110:111]
	global_store_dwordx4 v[106:107], v[142:145], off
	ds_write_b128 v228, v[110:113]
	ds_read_b128 v[110:113], v227 offset:8720
	ds_read_b128 v[114:117], v227 offset:8976
	ds_read_b128 v[118:121], v227 offset:9232
	ds_read_b128 v[122:125], v227 offset:9488
	ds_read_b128 v[126:129], v227 offset:9744
	v_lshlrev_b32_e32 v130, 16, v108
	s_waitcnt lgkmcnt(3)
	v_pk_mul_f32 v[104:105], v[104:105], v[116:117]
	v_pk_mul_f32 v[102:103], v[102:103], v[114:115]
	v_pk_fma_f32 v[96:97], v[96:97], v[112:113], v[104:105]
	v_pk_fma_f32 v[94:95], v[94:95], v[110:111], v[102:103]
	v_and_b32_e32 v131, 0xffff0000, v108
	v_lshlrev_b32_e32 v132, 16, v109
	v_and_b32_e32 v133, 0xffff0000, v109
	s_waitcnt lgkmcnt(2)
	v_pk_fma_f32 v[96:97], v[100:101], v[120:121], v[96:97]
	v_pk_fma_f32 v[94:95], v[98:99], v[118:119], v[94:95]
	s_waitcnt lgkmcnt(1)
	v_pk_fma_f32 v[96:97], v[124:125], v[132:133], v[96:97]
	v_pk_fma_f32 v[94:95], v[122:123], v[130:131], v[94:95]
	s_waitcnt lgkmcnt(0)
	v_pk_add_f32 v[96:97], v[128:129], v[96:97]
	v_pk_add_f32 v[94:95], v[126:127], v[94:95]
	global_store_dwordx4 v[106:107], v[130:133], off offset:16
	ds_write_b128 v228, v[94:97] offset:16
	ds_read_b128 v[94:97], v227 offset:8736
	ds_read_b128 v[98:101], v227 offset:8992
	ds_read_b128 v[102:105], v227 offset:9248
	ds_read_b128 v[108:111], v227 offset:9504
	ds_read_b128 v[112:115], v227 offset:9760
	s_waitcnt vmcnt(10)
	v_lshlrev_b32_e32 v116, 16, v78
	v_and_b32_e32 v117, 0xffff0000, v78
	v_lshlrev_b32_e32 v118, 16, v79
	v_and_b32_e32 v119, 0xffff0000, v79
	s_waitcnt lgkmcnt(3)
	v_pk_mul_f32 v[78:79], v[92:93], v[100:101]
	v_pk_mul_f32 v[90:91], v[90:91], v[98:99]
	v_pk_fma_f32 v[78:79], v[84:85], v[96:97], v[78:79]
	v_pk_fma_f32 v[82:83], v[82:83], v[94:95], v[90:91]
	s_waitcnt lgkmcnt(2)
	v_pk_fma_f32 v[78:79], v[88:89], v[104:105], v[78:79]
	v_pk_fma_f32 v[82:83], v[86:87], v[102:103], v[82:83]
	s_waitcnt lgkmcnt(1)
	v_pk_fma_f32 v[78:79], v[110:111], v[118:119], v[78:79]
	v_pk_fma_f32 v[82:83], v[108:109], v[116:117], v[82:83]
	s_waitcnt lgkmcnt(0)
	v_pk_add_f32 v[84:85], v[114:115], v[78:79]
	v_pk_add_f32 v[82:83], v[112:113], v[82:83]
	global_store_dwordx4 v[106:107], v[116:119], off offset:32
	ds_write_b128 v228, v[82:85] offset:32
	ds_read_b128 v[82:85], v227 offset:8752
	ds_read_b128 v[86:89], v227 offset:9008
	ds_read_b128 v[90:93], v227 offset:9264
	ds_read_b128 v[94:97], v227 offset:9520
	ds_read_b128 v[98:101], v227 offset:9776
	v_lshlrev_b32_e32 v78, 16, v80
	s_waitcnt lgkmcnt(3)
	v_pk_mul_f32 v[76:77], v[76:77], v[88:89]
	v_pk_mul_f32 v[74:75], v[74:75], v[86:87]
	v_pk_fma_f32 v[68:69], v[68:69], v[84:85], v[76:77]
	v_pk_fma_f32 v[66:67], v[66:67], v[82:83], v[74:75]
	v_and_b32_e32 v79, 0xffff0000, v80
	v_lshlrev_b32_e32 v80, 16, v81
	v_and_b32_e32 v81, 0xffff0000, v81
	s_waitcnt lgkmcnt(2)
	v_pk_fma_f32 v[68:69], v[72:73], v[92:93], v[68:69]
	v_pk_fma_f32 v[66:67], v[70:71], v[90:91], v[66:67]
	s_waitcnt lgkmcnt(1)
	v_pk_fma_f32 v[68:69], v[96:97], v[80:81], v[68:69]
	v_pk_fma_f32 v[66:67], v[94:95], v[78:79], v[66:67]
	s_waitcnt lgkmcnt(0)
	v_pk_add_f32 v[68:69], v[100:101], v[68:69]
	v_pk_add_f32 v[66:67], v[98:99], v[66:67]
	global_store_dwordx4 v[106:107], v[78:81], off offset:48
	ds_write_b128 v228, v[66:69] offset:48
	s_waitcnt lgkmcnt(0)
	ds_read_b128 v[66:69], v239
	ds_read_b128 v[70:73], v239 offset:16
	s_waitcnt lgkmcnt(1)
	v_cvt_pk_bf16_f32 v66, v66, v67
	v_cvt_pk_bf16_f32 v67, v68, v69
	s_waitcnt lgkmcnt(0)
	v_cvt_pk_bf16_f32 v68, v70, v71
	v_cvt_pk_bf16_f32 v69, v72, v73
	ds_read_b128 v[86:89], v239 offset:128
	ds_read_b128 v[90:93], v239 offset:144
	v_mfma_f32_16x16x32_bf16 v[70:73], v[66:69], v[34:37], 0
	s_waitcnt lgkmcnt(1)
	v_cvt_pk_bf16_f32 v110, v86, v87
	v_cvt_pk_bf16_f32 v111, v88, v89
	s_waitcnt lgkmcnt(0)
	v_cvt_pk_bf16_f32 v112, v90, v91
	v_cvt_pk_bf16_f32 v113, v92, v93
	ds_read2st64_b32 v[120:121], v232 offset0:39 offset1:40
	ds_read_b32 v123, v232 offset:10496
	v_mfma_f32_16x16x32_bf16 v[94:97], v[110:113], v[10:13], v[70:73]
	v_or_b32_e32 v114, s11, v229
	v_or_b32_e32 v122, s75, v223
	v_lshlrev_b32_e32 v116, 2, v122
	v_mfma_f32_16x16x32_bf16 v[78:81], v[66:69], v[42:45], 0
	v_mov_b32_e32 v117, v1
	s_waitcnt lgkmcnt(1)
	s_nop 1
	v_add_f32_e32 v94, v94, v120
	v_mul_f32_e32 v94, 0xbfb8aa3b, v94
	v_exp_f32_e32 v94, v94
	v_mfma_f32_16x16x32_bf16 v[98:101], v[66:69], v[50:53], 0
	v_lshl_add_u64 v[118:119], s[14:15], 0, v[116:117]
	v_ashrrev_i32_e32 v115, 31, v114
	v_add_f32_e32 v94, 1.0, v94
	v_rcp_f32_e32 v94, v94
	v_mfma_f32_16x16x32_bf16 v[86:89], v[110:113], v[22:25], v[78:81]
	v_mul_f32_e32 v94, 0xc1000000, v94
	s_waitcnt lgkmcnt(0)
; __device__ __forceinline__ unsigned cvt_pk_bf16(float lo, float hi) { unsigned r; asm volatile("v_cvt_pk_bf16_f32 %0, %1, %2" : "=v"(r) : "v"(lo), "v"(hi)); return r; }
; __device__ __forceinline__ float sigmoidf_(float x) { return __builtin_amdgcn_rcpf(1.0f + __expf(-x)); }
; __device__ __forceinline__ void scan_phase(KP p, int l, LAS unsigned char* lds) {
;     ...
; #pragma unroll
;             for (int n = 0; n < 4; ++n) {
;                 const int cc = 16 * n + fr, ch = hc0 + cc;
;                 const float ba = CST[5 * 64 + cc], bx = CST[6 * 64 + cc], sp = CST[7 * 64 + cc];
; #pragma unroll
;                 for (int j = 0; j < 4; ++j) {
;                     const float xc = XC[(4 * fq + j) * 68 + cc];
;                     const float r = sigmoidf_(ar[n][j] + ba), ig = sigmoidf_(ai[n][j] + bx);
;                     const float a = __expf(-8.0f * r * sp);
;                     const float mult = sqrtf(fmaxf(1.0f - a * a, 0.f));
;                     const int sb = m0 - MP + 4 * fq + j;
;                     const float h0 = p->in[4][(size_t)(l * MS + sb) * D + ch];
;                     const float h = a * h0 + mult * ig * xc;
;                     const size_t o = (size_t)(m0 + 4 * fq + j) * D + ch; HLOC[o] = (bf16_t)(cvt_pk_bf16(h, 0.f) & 0xffffu); PCUM[o] = 0;
;                     p->out[O_SRG + (size_t)(l * MS + sb) * D + ch] = h; }
	v_mul_f32_e32 v94, v123, v94
	v_mul_f32_e32 v94, 0x3fb8aa3b, v94
	v_exp_f32_e32 v94, v94
	v_mfma_f32_16x16x32_bf16 v[78:81], v[110:113], v[30:33], v[98:101]
	s_nop 2
	v_fma_f32 v98, -v94, v94, 1.0
	v_max_f32_e32 v98, 0, v98
	s_nop 0
	s_nop 0
	v_mfma_f32_16x16x32_bf16 v[74:77], v[66:69], v[38:41], 0
	ds_read_b32 v100, v241
	v_mfma_f32_16x16x32_bf16 v[102:105], v[66:69], v[54:57], 0
	s_nop 0
	v_mfma_f32_16x16x32_bf16 v[82:85], v[66:69], v[46:49], 0
	v_mfma_f32_16x16x32_bf16 v[106:109], v[66:69], v[62:65], 0
	v_mfma_f32_16x16x32_bf16 v[66:69], v[66:69], v[58:61], 0
	v_mfma_f32_16x16x32_bf16 v[90:93], v[110:113], v[14:17], v[74:77]
	v_mfma_f32_16x16x32_bf16 v[74:77], v[110:113], v[18:21], v[102:105]
	s_nop 2
	s_nop 0
	v_mfma_f32_16x16x32_bf16 v[82:85], v[110:113], v[26:29], v[82:85]
	s_nop 1
	v_add_f32_e32 v90, v90, v121
	v_mul_f32_e32 v90, 0xbfb8aa3b, v90
	v_exp_f32_e32 v90, v90
	v_mfma_f32_16x16x32_bf16 v[70:73], v[110:113], v[6:9], v[106:109]
	v_add_f32_e32 v91, v91, v121
	v_mul_f32_e32 v91, 0xbfb8aa3b, v91
	v_add_f32_e32 v90, 1.0, v90
	v_mfma_f32_16x16x32_bf16 v[66:69], v[110:113], v[2:5], v[66:69]
	v_add_u32_e32 v110, s10, v230
	v_ashrrev_i32_e32 v111, 31, v110
	v_lshlrev_b64 v[106:107], 12, v[110:111]
	v_rcp_f32_e32 v90, v90
	v_lshlrev_b64 v[102:103], 10, v[114:115]
	v_exp_f32_e32 v91, v91
	v_sqrt_f32_e32 v101, v98
	s_nop 0
	v_lshl_add_u64 v[98:99], v[118:119], 0, v[106:107]
	s_mov_b64 s[98:99], 0x1000
	v_lshl_add_u64 v[164:165], v[98:99], 0, s[98:99]
	s_mov_b64 s[98:99], 0x2000
	v_lshl_add_u64 v[166:167], v[98:99], 0, s[98:99]
	s_mov_b64 s[98:99], 0x3000
	v_lshl_add_u64 v[168:169], v[98:99], 0, s[98:99]
	global_load_dword v148, v[98:99], off
	global_load_dword v149, v[164:165], off
	global_load_dword v150, v[166:167], off
	global_load_dword v151, v[168:169], off
	global_load_dword v152, v[98:99], off offset:64
	global_load_dword v153, v[164:165], off offset:64
	global_load_dword v154, v[166:167], off offset:64
	global_load_dword v155, v[168:169], off offset:64
	global_load_dword v156, v[98:99], off offset:128
	global_load_dword v157, v[164:165], off offset:128
	global_load_dword v158, v[166:167], off offset:128
	global_load_dword v159, v[168:169], off offset:128
	global_load_dword v160, v[98:99], off offset:192
	global_load_dword v161, v[164:165], off offset:192
	global_load_dword v162, v[166:167], off offset:192
	global_load_dword v163, v[168:169], off offset:192
	v_mul_f32_e32 v90, v90, v101
	s_waitcnt lgkmcnt(0)
	v_mul_f32_e32 v90, v100, v90
	v_mov_b32_e32 v99, v103
	v_add_f32_e32 v91, 1.0, v91
	v_add_f32_e32 v92, v92, v121
	v_mul_f32_e32 v92, 0xbfb8aa3b, v92
	v_exp_f32_e32 v92, v92
	v_add_f32_e32 v93, v93, v121
	v_mul_f32_e32 v93, 0xbfb8aa3b, v93
	v_exp_f32_e32 v93, v93
	v_add_f32_e32 v92, 1.0, v92
	v_rcp_f32_e32 v92, v92
	v_add_f32_e32 v93, 1.0, v93
	s_waitcnt vmcnt(15)
	v_mov_b32_e32 v98, v148
	v_fmac_f32_e32 v90, v98, v94
	v_or_b32_e32 v98, v102, v122
	v_lshlrev_b64 v[98:99], 1, v[98:99]
	v_lshl_add_u64 v[100:101], v[98:99], 1, s[62:63]
	v_cvt_pk_bf16_f32 v94, v90, v1
	v_lshl_add_u64 v[98:99], s[12:13], 0, v[106:107]
	v_lshl_add_u64 v[98:99], v[98:99], 0, s[18:19]
	global_store_dword v[100:101], v94, off
	v_lshl_add_u64 v[100:101], v[98:99], 0, v[116:117]
	global_store_dword v[100:101], v90, off
	v_add_f32_e32 v90, v95, v120
	v_mul_f32_e32 v90, 0xbfb8aa3b, v90
	v_exp_f32_e32 v90, v90
	v_rcp_f32_e32 v95, v91
	ds_read_b32 v94, v241 offset:272
	v_add_f32_e32 v90, 1.0, v90
	v_rcp_f32_e32 v90, v90
	s_nop 0
	v_mul_f32_e32 v90, 0xc1000000, v90
	v_mul_f32_e32 v90, v123, v90
	v_mul_f32_e32 v90, 0x3fb8aa3b, v90
	v_exp_f32_e32 v100, v90
	s_nop 0
	v_fma_f32 v90, -v100, v100, 1.0
	v_max_f32_e32 v90, 0, v90
	s_nop 0
	s_nop 0
	s_nop 0
	s_nop 1
	s_nop 1
	v_sqrt_f32_e32 v101, v90
	s_nop 0
	v_or_b32_e32 v90, 1, v110
	v_ashrrev_i32_e32 v91, 31, v90
	v_lshlrev_b64 v[112:113], 12, v[90:91]
	v_lshl_add_u64 v[90:91], v[118:119], 0, v[112:113]
	v_mul_f32_e32 v91, v95, v101
	s_waitcnt lgkmcnt(0)
	v_mul_f32_e32 v104, v94, v91
	s_waitcnt vmcnt(16)
	v_mov_b32_e32 v90, v149
	v_fmac_f32_e32 v104, v100, v90
	v_or_b32_e32 v90, 1, v114
	v_ashrrev_i32_e32 v91, 31, v90
	v_lshlrev_b64 v[100:101], 10, v[90:91]
	v_or_b32_e32 v90, v100, v122
	v_mov_b32_e32 v91, v101
	v_lshlrev_b64 v[90:91], 1, v[90:91]
	v_lshl_add_u64 v[94:95], v[90:91], 1, s[62:63]
	v_cvt_pk_bf16_f32 v105, v104, v1
	v_lshl_add_u64 v[90:91], s[12:13], 0, v[112:113]
	v_lshl_add_u64 v[90:91], v[90:91], 0, s[18:19]
	global_store_dword v[94:95], v105, off
	v_lshl_add_u64 v[94:95], v[90:91], 0, v[116:117]
	global_store_dword v[94:95], v104, off
	v_add_f32_e32 v94, v96, v120
	v_mul_f32_e32 v94, 0xbfb8aa3b, v94
	v_exp_f32_e32 v94, v94
	ds_read_b32 v104, v241 offset:544
	v_add_f32_e32 v94, 1.0, v94
	v_rcp_f32_e32 v94, v94
	s_nop 0
	v_mul_f32_e32 v94, 0xc1000000, v94
	v_mul_f32_e32 v94, v123, v94
	v_mul_f32_e32 v94, 0x3fb8aa3b, v94
	v_exp_f32_e32 v96, v94
	s_nop 0
	v_fma_f32 v94, -v96, v96, 1.0
	v_max_f32_e32 v94, 0, v94
	s_nop 0
	s_nop 0
	s_nop 0
	s_nop 1
	s_nop 1
	v_sqrt_f32_e32 v105, v94
	s_nop 0
	v_or_b32_e32 v94, 2, v110
	v_ashrrev_i32_e32 v95, 31, v94
	v_lshlrev_b64 v[108:109], 12, v[94:95]
	v_lshl_add_u64 v[94:95], v[118:119], 0, v[108:109]
	v_mul_f32_e32 v92, v92, v105
	s_waitcnt vmcnt(17)
	v_mov_b32_e32 v94, v150
	v_mul_f32_e32 v96, v96, v94
	v_or_b32_e32 v94, 2, v114
	v_ashrrev_i32_e32 v95, 31, v94
	s_waitcnt lgkmcnt(0)
; __device__ __forceinline__ unsigned cvt_pk_bf16(float lo, float hi) { unsigned r; asm volatile("v_cvt_pk_bf16_f32 %0, %1, %2" : "=v"(r) : "v"(lo), "v"(hi)); return r; }
; __device__ __forceinline__ float sigmoidf_(float x) { return __builtin_amdgcn_rcpf(1.0f + __expf(-x)); }
; __device__ __forceinline__ void scan_phase(KP p, int l, LAS unsigned char* lds) {
;     ...
; #pragma unroll
;             for (int n = 0; n < 4; ++n) {
;                 const int cc = 16 * n + fr, ch = hc0 + cc;
;                 const float ba = CST[5 * 64 + cc], bx = CST[6 * 64 + cc], sp = CST[7 * 64 + cc];
; #pragma unroll
;                 for (int j = 0; j < 4; ++j) {
;                     const float xc = XC[(4 * fq + j) * 68 + cc];
;                     const float r = sigmoidf_(ar[n][j] + ba), ig = sigmoidf_(ai[n][j] + bx);
;                     const float a = __expf(-8.0f * r * sp);
;                     const float mult = sqrtf(fmaxf(1.0f - a * a, 0.f));
;                     const int sb = m0 - MP + 4 * fq + j;
;                     const float h0 = p->in[4][(size_t)(l * MS + sb) * D + ch];
;                     const float h = a * h0 + mult * ig * xc;
;                     const size_t o = (size_t)(m0 + 4 * fq + j) * D + ch; HLOC[o] = (bf16_t)(cvt_pk_bf16(h, 0.f) & 0xffffu); PCUM[o] = 0;
;                     p->out[O_SRG + (size_t)(l * MS + sb) * D + ch] = h; }
	v_fmac_f32_e32 v96, v92, v104
	v_lshlrev_b64 v[104:105], 10, v[94:95]
	v_or_b32_e32 v94, v104, v122
	v_mov_b32_e32 v95, v105
	v_lshlrev_b64 v[94:95], 1, v[94:95]
	v_cvt_pk_bf16_f32 v92, v96, v1
	v_lshl_add_u64 v[124:125], v[94:95], 1, s[62:63]
	global_store_dword v[124:125], v92, off
	v_add_f32_e32 v92, v97, v120
	v_mul_f32_e32 v92, 0xbfb8aa3b, v92
	v_exp_f32_e32 v92, v92
	v_rcp_f32_e32 v97, v93
	v_add_f32_e32 v92, 1.0, v92
	v_rcp_f32_e32 v92, v92
	v_lshl_add_u64 v[94:95], s[12:13], 0, v[108:109]
	v_lshl_add_u64 v[94:95], v[94:95], 0, s[18:19]
	v_lshl_add_u64 v[124:125], v[94:95], 0, v[116:117]
	v_mul_f32_e32 v92, 0xc1000000, v92
	v_mul_f32_e32 v92, v123, v92
	v_mul_f32_e32 v92, 0x3fb8aa3b, v92
	v_exp_f32_e32 v115, v92
	global_store_dword v[124:125], v96, off
	ds_read_b32 v96, v241 offset:816
	v_fma_f32 v92, -v115, v115, 1.0
	v_max_f32_e32 v92, 0, v92
	s_nop 0
	s_nop 0
	s_nop 0
	s_nop 1
	s_nop 1
	v_sqrt_f32_e32 v120, v92
	s_nop 0
	v_or_b32_e32 v92, 3, v110
	v_ashrrev_i32_e32 v93, 31, v92
	v_lshlrev_b64 v[110:111], 12, v[92:93]
	v_lshl_add_u64 v[92:93], v[118:119], 0, v[110:111]
	s_waitcnt vmcnt(18)
	v_mov_b32_e32 v92, v151
	v_mul_f32_e32 v118, v115, v92
	v_mul_f32_e32 v92, v97, v120
	s_waitcnt lgkmcnt(0)
	v_fmac_f32_e32 v118, v92, v96
	v_or_b32_e32 v92, 3, v114
	v_ashrrev_i32_e32 v93, 31, v92
	v_lshlrev_b64 v[96:97], 10, v[92:93]
	v_or_b32_e32 v92, v96, v122
	v_mov_b32_e32 v93, v97
	v_lshlrev_b64 v[92:93], 1, v[92:93]
	v_lshl_add_u64 v[114:115], v[92:93], 1, s[62:63]
	v_cvt_pk_bf16_f32 v119, v118, v1
	v_lshl_add_u64 v[92:93], s[12:13], 0, v[110:111]
	v_lshl_add_u64 v[92:93], v[92:93], 0, s[18:19]
	global_store_dword v[114:115], v119, off
	v_lshl_add_u64 v[114:115], v[92:93], 0, v[116:117]
	global_store_dword v[114:115], v118, off
	v_add_u32_e32 v114, 64, v232
	ds_read2st64_b32 v[118:119], v114 offset0:39 offset1:40
	ds_read_b32 v121, v232 offset:10560
	v_add_lshl_u32 v114, s75, v223, 2
	v_mov_b32_e32 v115, v1
	v_lshl_add_u64 v[114:115], s[14:15], 0, v[114:115]
	s_waitcnt lgkmcnt(1)
	v_add_f32_e32 v86, v86, v118
	v_mul_f32_e32 v86, 0xbfb8aa3b, v86
	v_exp_f32_e32 v86, v86
	v_lshl_add_u64 v[106:107], v[114:115], 0, v[106:107]
	v_add_f32_e32 v82, v82, v119
	v_mul_f32_e32 v82, 0xbfb8aa3b, v82
	v_add_f32_e32 v86, 1.0, v86
	v_rcp_f32_e32 v86, v86
	v_exp_f32_e32 v82, v82
	ds_read_b32 v116, v241 offset:64
	v_or_b32_e32 v120, s75, v233
	v_mul_f32_e32 v86, 0xc1000000, v86
	s_waitcnt lgkmcnt(1)
	v_mul_f32_e32 v86, v121, v86
	v_mul_f32_e32 v86, 0x3fb8aa3b, v86
	v_exp_f32_e32 v86, v86
	v_add_f32_e32 v82, 1.0, v82
	v_rcp_f32_e32 v82, v82
	v_add_f32_e32 v83, v83, v119
	v_fma_f32 v117, -v86, v86, 1.0
	v_max_f32_e32 v117, 0, v117
	v_mul_f32_e32 v83, 0xbfb8aa3b, v83
	v_exp_f32_e32 v83, v83
	v_add_f32_e32 v84, v84, v119
	v_mul_f32_e32 v84, 0xbfb8aa3b, v84
	v_add_f32_e32 v83, 1.0, v83
	v_exp_f32_e32 v84, v84
	v_add_f32_e32 v85, v85, v119
	v_add_f32_e32 v84, 1.0, v84
	v_rcp_f32_e32 v84, v84
	v_sqrt_f32_e32 v117, v117
	s_nop 0
	v_mul_f32_e32 v82, v82, v117
	s_waitcnt lgkmcnt(0)
	v_mul_f32_e32 v82, v116, v82
	v_or_b32_e32 v116, v102, v120
	v_mov_b32_e32 v117, v103
	v_lshlrev_b64 v[116:117], 1, v[116:117]
	v_mul_f32_e32 v85, 0xbfb8aa3b, v85
	v_exp_f32_e32 v85, v85
	s_waitcnt vmcnt(19)
	v_mov_b32_e32 v122, v152
	v_fmac_f32_e32 v82, v122, v86
	v_lshl_add_u64 v[122:123], v[116:117], 1, s[62:63]
	v_cvt_pk_bf16_f32 v86, v82, v1
	v_lshlrev_b32_e32 v116, 2, v120
	v_mov_b32_e32 v117, v1
	global_store_dword v[122:123], v86, off
	v_lshl_add_u64 v[122:123], v[98:99], 0, v[116:117]
	global_store_dword v[122:123], v82, off
	v_add_f32_e32 v82, v87, v118
	v_mul_f32_e32 v82, 0xbfb8aa3b, v82
	v_exp_f32_e32 v82, v82
	v_rcp_f32_e32 v87, v83
	ds_read_b32 v86, v241 offset:336
	v_add_f32_e32 v85, 1.0, v85
	v_add_f32_e32 v82, 1.0, v82
	v_rcp_f32_e32 v82, v82
	s_nop 0
	v_mul_f32_e32 v82, 0xc1000000, v82
	v_mul_f32_e32 v82, v121, v82
	v_mul_f32_e32 v82, 0x3fb8aa3b, v82
	v_exp_f32_e32 v122, v82
	s_nop 0
	v_fma_f32 v82, -v122, v122, 1.0
	v_max_f32_e32 v82, 0, v82
	s_nop 0
	s_nop 0
	s_nop 0
	s_nop 1
	s_nop 1
	v_sqrt_f32_e32 v123, v82
	s_nop 0
	v_lshl_add_u64 v[82:83], v[114:115], 0, v[112:113]
	v_mul_f32_e32 v87, v87, v123
	s_waitcnt lgkmcnt(0)
	v_mul_f32_e32 v123, v86, v87
	v_or_b32_e32 v86, v100, v120
	v_mov_b32_e32 v87, v101
	v_lshlrev_b64 v[86:87], 1, v[86:87]
	s_waitcnt vmcnt(20)
	v_mov_b32_e32 v112, v153
	v_fmac_f32_e32 v123, v122, v112
	v_lshl_add_u64 v[112:113], v[86:87], 1, s[62:63]
	v_cvt_pk_bf16_f32 v122, v123, v1
	v_lshl_add_u64 v[86:87], v[90:91], 0, v[116:117]
	global_store_dword v[86:87], v123, off
	v_add_f32_e32 v86, v88, v118
	v_mul_f32_e32 v86, 0xbfb8aa3b, v86
	v_exp_f32_e32 v86, v86
	global_store_dword v[112:113], v122, off
	ds_read_b32 v112, v241 offset:608
	v_add_f32_e32 v86, 1.0, v86
	v_rcp_f32_e32 v86, v86
	s_nop 0
	v_mul_f32_e32 v86, 0xc1000000, v86
	v_mul_f32_e32 v86, v121, v86
	v_mul_f32_e32 v86, 0x3fb8aa3b, v86
	v_exp_f32_e32 v88, v86
	s_nop 0
	v_fma_f32 v86, -v88, v88, 1.0
	v_max_f32_e32 v86, 0, v86
	s_nop 0
	s_nop 0
	s_nop 0
	s_nop 1
	s_nop 1
	v_sqrt_f32_e32 v113, v86
	s_nop 0
	v_lshl_add_u64 v[86:87], v[114:115], 0, v[108:109]
	v_mov_b32_e32 v109, v105
	v_mul_f32_e32 v84, v84, v113
	s_waitcnt vmcnt(21)
	v_mov_b32_e32 v108, v154
	v_mul_f32_e32 v88, v88, v108
	v_or_b32_e32 v108, v104, v120
	v_lshlrev_b64 v[108:109], 1, v[108:109]
	s_waitcnt lgkmcnt(0)
; __device__ __forceinline__ unsigned cvt_pk_bf16(float lo, float hi) { unsigned r; asm volatile("v_cvt_pk_bf16_f32 %0, %1, %2" : "=v"(r) : "v"(lo), "v"(hi)); return r; }
; __device__ __forceinline__ float sigmoidf_(float x) { return __builtin_amdgcn_rcpf(1.0f + __expf(-x)); }
; __device__ __forceinline__ void scan_phase(KP p, int l, LAS unsigned char* lds) {
;     ...
; #pragma unroll
;             for (int n = 0; n < 4; ++n) {
;                 const int cc = 16 * n + fr, ch = hc0 + cc;
;                 const float ba = CST[5 * 64 + cc], bx = CST[6 * 64 + cc], sp = CST[7 * 64 + cc];
; #pragma unroll
;                 for (int j = 0; j < 4; ++j) {
;                     const float xc = XC[(4 * fq + j) * 68 + cc];
;                     const float r = sigmoidf_(ar[n][j] + ba), ig = sigmoidf_(ai[n][j] + bx);
;                     const float a = __expf(-8.0f * r * sp);
;                     const float mult = sqrtf(fmaxf(1.0f - a * a, 0.f));
;                     const int sb = m0 - MP + 4 * fq + j;
;                     const float h0 = p->in[4][(size_t)(l * MS + sb) * D + ch];
;                     const float h = a * h0 + mult * ig * xc;
;                     const size_t o = (size_t)(m0 + 4 * fq + j) * D + ch; HLOC[o] = (bf16_t)(cvt_pk_bf16(h, 0.f) & 0xffffu); PCUM[o] = 0;
;                     p->out[O_SRG + (size_t)(l * MS + sb) * D + ch] = h; }
	v_fmac_f32_e32 v88, v84, v112
	v_cvt_pk_bf16_f32 v84, v88, v1
	v_lshl_add_u64 v[112:113], v[108:109], 1, s[62:63]
	global_store_dword v[112:113], v84, off
	v_add_f32_e32 v84, v89, v118
	v_mul_f32_e32 v84, 0xbfb8aa3b, v84
	v_exp_f32_e32 v84, v84
	v_lshl_add_u64 v[108:109], v[94:95], 0, v[116:117]
	v_add_f32_e32 v84, 1.0, v84
	v_rcp_f32_e32 v84, v84
	global_store_dword v[108:109], v88, off
	v_rcp_f32_e32 v89, v85
	ds_read_b32 v88, v241 offset:880
	v_mul_f32_e32 v84, 0xc1000000, v84
	v_mul_f32_e32 v84, v121, v84
	v_mul_f32_e32 v84, 0x3fb8aa3b, v84
	v_exp_f32_e32 v108, v84
	s_nop 0
	v_fma_f32 v84, -v108, v108, 1.0
	v_max_f32_e32 v84, 0, v84
	s_nop 0
	s_nop 0
	s_nop 0
	s_nop 1
	s_nop 1
	v_sqrt_f32_e32 v109, v84
	s_nop 0
	v_lshl_add_u64 v[84:85], v[114:115], 0, v[110:111]
	v_mul_f32_e32 v89, v89, v109
	s_waitcnt vmcnt(22)
	v_mov_b32_e32 v110, v155
	v_mul_f32_e32 v110, v108, v110
	s_waitcnt lgkmcnt(0)
	v_fmac_f32_e32 v110, v89, v88
	v_or_b32_e32 v88, v96, v120
	v_mov_b32_e32 v89, v97
	v_lshlrev_b64 v[88:89], 1, v[88:89]
	v_lshl_add_u64 v[108:109], v[88:89], 1, s[62:63]
	v_cvt_pk_bf16_f32 v111, v110, v1
	v_lshl_add_u64 v[88:89], v[92:93], 0, v[116:117]
	global_store_dword v[108:109], v111, off
	global_store_dword v[88:89], v110, off
	v_add_u32_e32 v88, 0x80, v232
	ds_read2st64_b32 v[108:109], v88 offset0:39 offset1:40
	ds_read_b32 v111, v232 offset:10624
	ds_read_b32 v88, v241 offset:128
	v_or_b32_e32 v110, s75, v234
	s_waitcnt lgkmcnt(2)
	v_add_f32_e32 v78, v78, v108
	v_mul_f32_e32 v78, 0xbfb8aa3b, v78
	v_exp_f32_e32 v78, v78
	v_add_f32_e32 v74, v74, v109
	v_mul_f32_e32 v74, 0xbfb8aa3b, v74
	v_exp_f32_e32 v74, v74
	v_add_f32_e32 v78, 1.0, v78
	v_rcp_f32_e32 v78, v78
	v_add_f32_e32 v75, v75, v109
	v_add_f32_e32 v74, 1.0, v74
	v_rcp_f32_e32 v74, v74
	v_mul_f32_e32 v78, 0xc1000000, v78
	s_waitcnt lgkmcnt(1)
	v_mul_f32_e32 v78, v111, v78
	v_mul_f32_e32 v78, 0x3fb8aa3b, v78
	v_exp_f32_e32 v78, v78
	v_mul_f32_e32 v75, 0xbfb8aa3b, v75
	v_exp_f32_e32 v75, v75
	v_add_f32_e32 v76, v76, v109
	v_fma_f32 v89, -v78, v78, 1.0
	v_max_f32_e32 v89, 0, v89
	v_add_f32_e32 v75, 1.0, v75
	v_rcp_f32_e32 v75, v75
	v_mul_f32_e32 v76, 0xbfb8aa3b, v76
	v_exp_f32_e32 v76, v76
	s_nop 0
	v_add_f32_e32 v76, 1.0, v76
	v_rcp_f32_e32 v76, v76
	s_nop 0
	s_nop 1
	v_sqrt_f32_e32 v89, v89
	s_nop 0
	v_mul_f32_e32 v74, v74, v89
	s_waitcnt lgkmcnt(0)
	v_mul_f32_e32 v74, v88, v74
	v_or_b32_e32 v88, v102, v110
	v_mov_b32_e32 v89, v103
	v_lshlrev_b64 v[88:89], 1, v[88:89]
	s_waitcnt vmcnt(23)
	v_mov_b32_e32 v112, v156
	v_fmac_f32_e32 v74, v112, v78
	v_cvt_pk_bf16_f32 v78, v74, v1
	v_lshl_add_u64 v[112:113], v[88:89], 1, s[62:63]
	global_store_dword v[112:113], v78, off
	v_add_f32_e32 v78, v79, v108
	v_mul_f32_e32 v78, 0xbfb8aa3b, v78
	v_exp_f32_e32 v78, v78
	v_lshlrev_b32_e32 v88, 2, v110
	v_add_f32_e32 v78, 1.0, v78
	v_rcp_f32_e32 v78, v78
	v_mov_b32_e32 v89, v1
	v_lshl_add_u64 v[112:113], v[98:99], 0, v[88:89]
	global_store_dword v[112:113], v74, off
	v_mul_f32_e32 v78, 0xc1000000, v78
	v_mul_f32_e32 v78, v111, v78
	v_mul_f32_e32 v78, 0x3fb8aa3b, v78
	v_exp_f32_e32 v78, v78
	ds_read_b32 v74, v241 offset:400
	v_fma_f32 v79, -v78, v78, 1.0
	v_max_f32_e32 v79, 0, v79
	s_nop 0
	s_nop 0
	s_nop 0
	s_nop 1
	s_nop 1
	v_sqrt_f32_e32 v79, v79
	s_nop 0
	v_mul_f32_e32 v75, v75, v79
	s_waitcnt lgkmcnt(0)
	v_mul_f32_e32 v113, v74, v75
	v_or_b32_e32 v74, v100, v110
	v_mov_b32_e32 v75, v101
	v_lshlrev_b64 v[74:75], 1, v[74:75]
	s_waitcnt vmcnt(24)
	v_mov_b32_e32 v112, v157
	v_fmac_f32_e32 v113, v78, v112
	v_lshl_add_u64 v[78:79], v[74:75], 1, s[62:63]
	v_cvt_pk_bf16_f32 v112, v113, v1
	v_lshl_add_u64 v[74:75], v[90:91], 0, v[88:89]
	global_store_dword v[74:75], v113, off
	v_add_f32_e32 v75, v80, v108
	v_mul_f32_e32 v75, 0xbfb8aa3b, v75
	v_exp_f32_e32 v75, v75
	global_store_dword v[78:79], v112, off
	ds_read_b32 v74, v241 offset:672
	v_add_f32_e32 v75, 1.0, v75
	v_rcp_f32_e32 v75, v75
	s_nop 0
	v_mul_f32_e32 v75, 0xc1000000, v75
	v_mul_f32_e32 v75, v111, v75
	v_mul_f32_e32 v75, 0x3fb8aa3b, v75
	v_exp_f32_e32 v75, v75
	s_nop 0
	v_fma_f32 v78, -v75, v75, 1.0
	v_max_f32_e32 v78, 0, v78
	s_nop 0
	s_nop 0
	s_nop 0
	s_nop 1
	s_nop 1
	v_sqrt_f32_e32 v78, v78
	s_nop 0
	s_waitcnt vmcnt(25)
	v_mov_b32_e32 v79, v158
	v_mul_f32_e32 v80, v75, v79
	v_mul_f32_e32 v75, v76, v78
	s_waitcnt lgkmcnt(0)
	v_fmac_f32_e32 v80, v75, v74
	v_or_b32_e32 v74, v104, v110
	v_mov_b32_e32 v75, v105
	v_lshlrev_b64 v[74:75], 1, v[74:75]
	v_lshl_add_u64 v[78:79], v[74:75], 1, s[62:63]
	v_cvt_pk_bf16_f32 v76, v80, v1
	v_lshl_add_u64 v[74:75], v[94:95], 0, v[88:89]
	global_store_dword v[74:75], v80, off
	v_add_f32_e32 v75, v81, v108
	v_mul_f32_e32 v75, 0xbfb8aa3b, v75
	v_exp_f32_e32 v75, v75
	global_store_dword v[78:79], v76, off
	v_add_f32_e32 v76, v77, v109
	v_mul_f32_e32 v76, 0xbfb8aa3b, v76
	v_add_f32_e32 v75, 1.0, v75
	v_rcp_f32_e32 v75, v75
	v_exp_f32_e32 v76, v76
	ds_read_b32 v74, v241 offset:944
	v_mul_f32_e32 v75, 0xc1000000, v75
	v_mul_f32_e32 v75, v111, v75
	v_mul_f32_e32 v75, 0x3fb8aa3b, v75
	v_exp_f32_e32 v75, v75
	v_add_f32_e32 v76, 1.0, v76
	v_rcp_f32_e32 v76, v76
	v_fma_f32 v77, -v75, v75, 1.0
	v_max_f32_e32 v77, 0, v77
	s_nop 0
	s_nop 0
	s_nop 0
	s_nop 1
	s_nop 1
	v_sqrt_f32_e32 v77, v77
	s_nop 0
	s_waitcnt vmcnt(26)
; __device__ __forceinline__ unsigned cvt_pk_bf16(float lo, float hi) { unsigned r; asm volatile("v_cvt_pk_bf16_f32 %0, %1, %2" : "=v"(r) : "v"(lo), "v"(hi)); return r; }
; __device__ __forceinline__ float sigmoidf_(float x) { return __builtin_amdgcn_rcpf(1.0f + __expf(-x)); }
; __device__ __forceinline__ void scan_phase(KP p, int l, LAS unsigned char* lds) {
;     ...
; #pragma unroll
;             for (int n = 0; n < 4; ++n) {
;                 const int cc = 16 * n + fr, ch = hc0 + cc;
;                 const float ba = CST[5 * 64 + cc], bx = CST[6 * 64 + cc], sp = CST[7 * 64 + cc];
; #pragma unroll
;                 for (int j = 0; j < 4; ++j) {
;                     const float xc = XC[(4 * fq + j) * 68 + cc];
;                     const float r = sigmoidf_(ar[n][j] + ba), ig = sigmoidf_(ai[n][j] + bx);
;                     const float a = __expf(-8.0f * r * sp);
;                     const float mult = sqrtf(fmaxf(1.0f - a * a, 0.f));
;                     const int sb = m0 - MP + 4 * fq + j;
;                     const float h0 = p->in[4][(size_t)(l * MS + sb) * D + ch];
;                     const float h = a * h0 + mult * ig * xc;
;                     const size_t o = (size_t)(m0 + 4 * fq + j) * D + ch; HLOC[o] = (bf16_t)(cvt_pk_bf16(h, 0.f) & 0xffffu); PCUM[o] = 0;
;                     p->out[O_SRG + (size_t)(l * MS + sb) * D + ch] = h; }
	v_mov_b32_e32 v78, v159
	v_mul_f32_e32 v78, v75, v78
	v_mul_f32_e32 v75, v76, v77
	s_waitcnt lgkmcnt(0)
	v_fmac_f32_e32 v78, v75, v74
	v_or_b32_e32 v74, v96, v110
	v_mov_b32_e32 v75, v97
	v_lshlrev_b64 v[74:75], 1, v[74:75]
	v_lshl_add_u64 v[76:77], v[74:75], 1, s[62:63]
	v_cvt_pk_bf16_f32 v79, v78, v1
	v_lshl_add_u64 v[74:75], v[92:93], 0, v[88:89]
	global_store_dword v[76:77], v79, off
	global_store_dword v[74:75], v78, off
	v_add_u32_e32 v74, 0xc0, v232
	ds_read2st64_b32 v[76:77], v74 offset0:39 offset1:40
	ds_read_b32 v79, v232 offset:10688
	ds_read_b32 v74, v241 offset:192
	v_or_b32_e32 v78, s75, v235
	v_or_b32_e32 v102, v102, v78
	s_waitcnt lgkmcnt(2)
	v_add_f32_e32 v70, v70, v76
	v_mul_f32_e32 v70, 0xbfb8aa3b, v70
	v_exp_f32_e32 v70, v70
	v_add_f32_e32 v66, v66, v77
	v_mul_f32_e32 v66, 0xbfb8aa3b, v66
	v_exp_f32_e32 v66, v66
	v_add_f32_e32 v70, 1.0, v70
	v_rcp_f32_e32 v70, v70
	v_add_f32_e32 v67, v67, v77
	v_add_f32_e32 v66, 1.0, v66
	v_rcp_f32_e32 v66, v66
	v_mul_f32_e32 v70, 0xc1000000, v70
	s_waitcnt lgkmcnt(1)
	v_mul_f32_e32 v70, v79, v70
	v_mul_f32_e32 v70, 0x3fb8aa3b, v70
	v_exp_f32_e32 v70, v70
	v_mul_f32_e32 v67, 0xbfb8aa3b, v67
	v_exp_f32_e32 v67, v67
	v_or_b32_e32 v100, v100, v78
	v_fma_f32 v75, -v70, v70, 1.0
	v_max_f32_e32 v75, 0, v75
	v_add_f32_e32 v67, 1.0, v67
	v_rcp_f32_e32 v67, v67
	v_add_f32_e32 v68, v68, v77
	v_mul_f32_e32 v68, 0xbfb8aa3b, v68
	v_exp_f32_e32 v68, v68
	s_nop 0
	v_add_f32_e32 v68, 1.0, v68
	v_rcp_f32_e32 v68, v68
	v_or_b32_e32 v104, v104, v78
	v_or_b32_e32 v96, v96, v78
	v_sqrt_f32_e32 v75, v75
	s_nop 0
	v_mul_f32_e32 v66, v66, v75
	s_waitcnt lgkmcnt(0)
	v_mul_f32_e32 v66, v74, v66
	v_lshlrev_b64 v[74:75], 1, v[102:103]
	s_waitcnt vmcnt(27)
	v_mov_b32_e32 v80, v160
	v_fmac_f32_e32 v66, v80, v70
	v_cvt_pk_bf16_f32 v70, v66, v1
	v_lshl_add_u64 v[80:81], v[74:75], 1, s[62:63]
	global_store_dword v[80:81], v70, off
	v_add_f32_e32 v70, v71, v76
	v_mul_f32_e32 v70, 0xbfb8aa3b, v70
	v_exp_f32_e32 v70, v70
	v_lshlrev_b32_e32 v74, 2, v78
	v_add_f32_e32 v70, 1.0, v70
	v_rcp_f32_e32 v70, v70
	v_mov_b32_e32 v75, v1
	v_lshl_add_u64 v[80:81], v[98:99], 0, v[74:75]
	global_store_dword v[80:81], v66, off
	v_mul_f32_e32 v70, 0xc1000000, v70
	v_mul_f32_e32 v70, v79, v70
	v_mul_f32_e32 v70, 0x3fb8aa3b, v70
	v_exp_f32_e32 v70, v70
	ds_read_b32 v66, v241 offset:464
	v_fma_f32 v71, -v70, v70, 1.0
	v_max_f32_e32 v71, 0, v71
	s_nop 0
	s_nop 0
	s_nop 0
	s_nop 1
	s_nop 1
	v_sqrt_f32_e32 v71, v71
	s_nop 0
	v_mul_f32_e32 v67, v67, v71
	s_waitcnt lgkmcnt(0)
	v_mul_f32_e32 v81, v66, v67
	v_lshlrev_b64 v[66:67], 1, v[100:101]
	s_waitcnt vmcnt(28)
	v_mov_b32_e32 v80, v161
	v_fmac_f32_e32 v81, v70, v80
	v_lshl_add_u64 v[70:71], v[66:67], 1, s[62:63]
	v_cvt_pk_bf16_f32 v80, v81, v1
	v_lshl_add_u64 v[66:67], v[90:91], 0, v[74:75]
	global_store_dword v[66:67], v81, off
	v_add_f32_e32 v67, v72, v76
	v_mul_f32_e32 v67, 0xbfb8aa3b, v67
	v_exp_f32_e32 v67, v67
	global_store_dword v[70:71], v80, off
	ds_read_b32 v66, v241 offset:736
	v_add_f32_e32 v67, 1.0, v67
	v_rcp_f32_e32 v67, v67
	s_nop 0
	v_mul_f32_e32 v67, 0xc1000000, v67
	v_mul_f32_e32 v67, v79, v67
	v_mul_f32_e32 v67, 0x3fb8aa3b, v67
	v_exp_f32_e32 v67, v67
	s_nop 0
	v_fma_f32 v70, -v67, v67, 1.0
	v_max_f32_e32 v70, 0, v70
	s_nop 0
	s_nop 0
	s_nop 0
	s_nop 1
	s_nop 1
	v_sqrt_f32_e32 v70, v70
	s_nop 0
	s_waitcnt vmcnt(29)
	v_mov_b32_e32 v71, v162
	v_mul_f32_e32 v72, v67, v71
	v_mul_f32_e32 v67, v68, v70
	s_waitcnt lgkmcnt(0)
	v_fmac_f32_e32 v72, v67, v66
	v_lshlrev_b64 v[66:67], 1, v[104:105]
	v_lshl_add_u64 v[70:71], v[66:67], 1, s[62:63]
	v_cvt_pk_bf16_f32 v68, v72, v1
	v_lshl_add_u64 v[66:67], v[94:95], 0, v[74:75]
	global_store_dword v[66:67], v72, off
	v_add_f32_e32 v67, v73, v76
	v_mul_f32_e32 v67, 0xbfb8aa3b, v67
	v_exp_f32_e32 v67, v67
	global_store_dword v[70:71], v68, off
	v_add_f32_e32 v68, v69, v77
	v_mul_f32_e32 v68, 0xbfb8aa3b, v68
	v_add_f32_e32 v67, 1.0, v67
	v_rcp_f32_e32 v67, v67
	v_exp_f32_e32 v68, v68
	ds_read_b32 v66, v241 offset:1008
	v_mul_f32_e32 v67, 0xc1000000, v67
	v_mul_f32_e32 v67, v79, v67
	v_mul_f32_e32 v67, 0x3fb8aa3b, v67
	v_exp_f32_e32 v67, v67
	v_add_f32_e32 v68, 1.0, v68
	v_rcp_f32_e32 v68, v68
	v_fma_f32 v69, -v67, v67, 1.0
	v_max_f32_e32 v69, 0, v69
	s_nop 0
	s_nop 0
	s_nop 0
	s_nop 1
	s_nop 1
	v_sqrt_f32_e32 v69, v69
	s_nop 0
	s_waitcnt vmcnt(30)
	v_mov_b32_e32 v70, v163
	v_mul_f32_e32 v70, v67, v70
	v_mul_f32_e32 v67, v68, v69
	s_waitcnt lgkmcnt(0)
	v_fmac_f32_e32 v70, v67, v66
	v_lshlrev_b64 v[66:67], 1, v[96:97]
	v_lshl_add_u64 v[68:69], v[66:67], 1, s[62:63]
	v_cvt_pk_bf16_f32 v71, v70, v1
	v_lshl_add_u64 v[66:67], v[92:93], 0, v[74:75]
	global_store_dword v[68:69], v71, off
	global_store_dword v[66:67], v70, off
	s_cbranch_execnz .LBB0_330
	s_branch .LBB0_334
